# rwkv pair_sync: poll interval s_sleep 2 (less issue interference from the waiting partner wave)
# speedup vs baseline: 1.0018x; 1.0018x over previous
; #define LAS __attribute__((address_space(3)))
; DI void pair_sync(volatile LAS int* fl, int half, int seq) {
;     asm volatile("s_waitcnt lgkmcnt(0)" ::: "memory");
;     fl[half] = seq;
;     while (fl[1 - half] < seq) __builtin_amdgcn_s_sleep(1);
;     asm volatile("s_waitcnt lgkmcnt(0)" ::: "memory");
; }
.LBB0_68:
	v_mov_b32_e32 v0, s9
	s_sleep 2
	ds_read_b32 v0, v0 offset:26116
	s_waitcnt lgkmcnt(0)
	v_cmp_ge_i32_e32 vcc, s23, v0
	s_cbranch_vccnz .LBB0_68

; #define LAS __attribute__((address_space(3)))
; DI void pair_sync(volatile LAS int* fl, int half, int seq) {
;     asm volatile("s_waitcnt lgkmcnt(0)" ::: "memory");
;     fl[half] = seq;
;     while (fl[1 - half] < seq) __builtin_amdgcn_s_sleep(1);
;     asm volatile("s_waitcnt lgkmcnt(0)" ::: "memory");
; }
.LBB0_78:
	v_mov_b32_e32 v2, s9
	s_sleep 2
	ds_read_b32 v2, v2 offset:26116
	s_waitcnt lgkmcnt(0)
	v_cmp_gt_i32_e32 vcc, s12, v2
	s_cbranch_vccnz .LBB0_78

; #define LAS __attribute__((address_space(3)))
; DI void pair_sync(volatile LAS int* fl, int half, int seq) {
;     asm volatile("s_waitcnt lgkmcnt(0)" ::: "memory");
;     fl[half] = seq;
;     while (fl[1 - half] < seq) __builtin_amdgcn_s_sleep(1);
;     asm volatile("s_waitcnt lgkmcnt(0)" ::: "memory");
; }
.LBB0_90:
	v_mov_b32_e32 v1, s9
	s_sleep 2
	ds_read_b32 v1, v1 offset:26116
	s_waitcnt lgkmcnt(0)
	v_cmp_gt_i32_e32 vcc, s12, v1
	s_cbranch_vccnz .LBB0_90

; #define LAS __attribute__((address_space(3)))
; DI void pair_sync(volatile LAS int* fl, int half, int seq) {
;     asm volatile("s_waitcnt lgkmcnt(0)" ::: "memory");
;     fl[half] = seq;
;     while (fl[1 - half] < seq) __builtin_amdgcn_s_sleep(1);
;     asm volatile("s_waitcnt lgkmcnt(0)" ::: "memory");
; }
.LBB0_96:
	v_mov_b32_e32 v0, s9
	s_sleep 2
	ds_read_b32 v0, v0 offset:26116
	s_waitcnt lgkmcnt(0)
	v_cmp_gt_i32_e32 vcc, s23, v0
	s_cbranch_vccnz .LBB0_96
